# v52
# speedup vs baseline: 1.0088x; 1.0036x over previous
.LBB0_73:
	s_cmp_eq_u32 s15, 0x30400
	s_mov_b32 s2, 0x10000
	s_and_b32 s2, s13, 0x10000
	s_xor_b32 s10, s2, 0x10000
	s_add_i32 s16, s21, s10
	s_add_i32 s17, s15, 0xfffd0000
	s_add_i32 s30, s16, 0x8000
	s_mov_b32 s10, s66
	s_mov_b32 s11, s67
	s_waitcnt lgkmcnt(0)
	v_add_u32_e32 v228, s2, v138
	v_add_u32_e32 v229, s2, v136
	ds_read_b128 v[132:135], v229 offset:0
	ds_read_b128 v[140:143], v229 offset:0x800
	ds_read_b128 v[144:147], v229 offset:0x1000
	ds_read_b128 v[148:151], v229 offset:0x1800
	ds_read_b128 v[152:155], v228 offset:0
	ds_read_b128 v[156:159], v228 offset:0x800
	s_setprio 1
	s_mov_b32 m0, s16
	s_nop 0
	buffer_load_dwordx4 v131, s[64:67], s17 offen lds
	s_mov_b32 m0, s30
	s_nop 0
	buffer_load_dwordx4 v131, s[8:11], s17 offen lds
	s_add_i32 m0, s16, 0x2000
	s_add_i32 s17, s15, 0xfffe0000
	buffer_load_dwordx4 v131, s[64:67], s17 offen lds
	s_add_i32 m0, s16, 0xa000
	s_nop 0
	buffer_load_dwordx4 v131, s[8:11], s17 offen lds
	s_add_i32 m0, s16, 0x4000
	s_add_i32 s17, s15, 0xffff0000
	buffer_load_dwordx4 v131, s[64:67], s17 offen lds
	ds_read_b128 v[160:163], v228 offset:0x1000
	v_xor_b32_e32 v176, 64, v228
	s_waitcnt lgkmcnt(2)
	v_mfma_f32_16x16x32_bf16 v[126:129], v[152:155], v[132:135], 0
	v_mfma_f32_16x16x32_bf16 v[122:125], v[152:155], v[140:143], 0
	v_mfma_f32_16x16x32_bf16 v[118:121], v[152:155], v[144:147], 0
	v_mfma_f32_16x16x32_bf16 v[114:117], v[152:155], v[148:151], 0
	s_add_i32 m0, s16, 0xc000
	s_nop 0
	buffer_load_dwordx4 v131, s[8:11], s17 offen lds
	ds_read_b128 v[152:155], v228 offset:0x1800
	s_waitcnt lgkmcnt(2)
	v_mfma_f32_16x16x32_bf16 v[110:113], v[156:159], v[132:135], 0
	v_mfma_f32_16x16x32_bf16 v[106:109], v[156:159], v[140:143], 0
	v_mfma_f32_16x16x32_bf16 v[102:105], v[156:159], v[144:147], 0
	v_mfma_f32_16x16x32_bf16 v[98:101], v[156:159], v[148:151], 0
	s_add_i32 m0, s16, 0x6000
	s_nop 0
	buffer_load_dwordx4 v131, s[64:67], s15 offen lds
	ds_read_b128 v[156:159], v228 offset:0x2000
	s_waitcnt lgkmcnt(2)
	v_mfma_f32_16x16x32_bf16 v[94:97], v[160:163], v[132:135], 0
	v_mfma_f32_16x16x32_bf16 v[90:93], v[160:163], v[140:143], 0
	v_mfma_f32_16x16x32_bf16 v[86:89], v[160:163], v[144:147], 0
	v_mfma_f32_16x16x32_bf16 v[82:85], v[160:163], v[148:151], 0
	s_add_i32 m0, s16, 0xe000
	s_nop 0
	buffer_load_dwordx4 v131, s[8:11], s15 offen lds
	ds_read_b128 v[160:163], v228 offset:0x2800
	s_waitcnt lgkmcnt(2)
	v_mfma_f32_16x16x32_bf16 v[78:81], v[152:155], v[132:135], 0
	v_mfma_f32_16x16x32_bf16 v[74:77], v[152:155], v[140:143], 0
	v_mfma_f32_16x16x32_bf16 v[70:73], v[152:155], v[144:147], 0
	v_mfma_f32_16x16x32_bf16 v[66:69], v[152:155], v[148:151], 0
	ds_read_b128 v[152:155], v228 offset:0x3000
	s_waitcnt lgkmcnt(2)
	v_mfma_f32_16x16x32_bf16 v[62:65], v[156:159], v[132:135], 0
	v_mfma_f32_16x16x32_bf16 v[58:61], v[156:159], v[140:143], 0
	v_mfma_f32_16x16x32_bf16 v[54:57], v[156:159], v[144:147], 0
	v_mfma_f32_16x16x32_bf16 v[50:53], v[156:159], v[148:151], 0
	ds_read_b128 v[156:159], v228 offset:0x3800
	s_waitcnt lgkmcnt(2)
	v_xor_b32_e32 v0, 64, v229
	v_mfma_f32_16x16x32_bf16 v[46:49], v[160:163], v[132:135], 0
	v_mfma_f32_16x16x32_bf16 v[42:45], v[160:163], v[140:143], 0
	v_mfma_f32_16x16x32_bf16 v[38:41], v[160:163], v[144:147], 0
	v_mfma_f32_16x16x32_bf16 v[34:37], v[160:163], v[148:151], 0
	ds_read_b128 v[160:163], v0 offset:0
	ds_read_b128 v[164:167], v0 offset:0x800
	ds_read_b128 v[168:171], v0 offset:0x1000
	s_waitcnt lgkmcnt(4)
	v_mfma_f32_16x16x32_bf16 v[30:33], v[152:155], v[132:135], 0
	v_mfma_f32_16x16x32_bf16 v[26:29], v[152:155], v[140:143], 0
	v_mfma_f32_16x16x32_bf16 v[22:25], v[152:155], v[144:147], 0
	v_mfma_f32_16x16x32_bf16 v[18:21], v[152:155], v[148:151], 0
	ds_read_b128 v[232:235], v0 offset:0x1800
	ds_read_b128 v[172:175], v176 offset:0
	ds_read_b128 v[202:205], v176 offset:0x800
	s_waitcnt lgkmcnt(6)
	v_mfma_f32_16x16x32_bf16 v[14:17], v[156:159], v[132:135], 0
	v_mfma_f32_16x16x32_bf16 v[10:13], v[156:159], v[140:143], 0
	v_mfma_f32_16x16x32_bf16 v[6:9], v[156:159], v[144:147], 0
	v_mfma_f32_16x16x32_bf16 v[2:5], v[156:159], v[148:151], 0
	ds_read_b128 v[132:135], v176 offset:0x1000
	ds_read_b128 v[236:239], v176 offset:0x2800
	s_waitcnt lgkmcnt(3)
	v_mfma_f32_16x16x32_bf16 v[126:129], v[172:175], v[160:163], v[126:129]
	v_mfma_f32_16x16x32_bf16 v[122:125], v[172:175], v[164:167], v[122:125]
	v_mfma_f32_16x16x32_bf16 v[118:121], v[172:175], v[168:171], v[118:121]
	v_mfma_f32_16x16x32_bf16 v[114:117], v[172:175], v[232:235], v[114:117]
	ds_read_b128 v[140:143], v176 offset:0x1800
	ds_read_b128 v[240:243], v176 offset:0x3000
	s_waitcnt lgkmcnt(4)
	v_mfma_f32_16x16x32_bf16 v[110:113], v[202:205], v[160:163], v[110:113]
	v_mfma_f32_16x16x32_bf16 v[106:109], v[202:205], v[164:167], v[106:109]
	v_mfma_f32_16x16x32_bf16 v[102:105], v[202:205], v[168:171], v[102:105]
	v_mfma_f32_16x16x32_bf16 v[98:101], v[202:205], v[232:235], v[98:101]
	ds_read_b128 v[144:147], v176 offset:0x2000
	ds_read_b128 v[244:247], v176 offset:0x3800
	s_waitcnt lgkmcnt(5)
	v_mfma_f32_16x16x32_bf16 v[94:97], v[132:135], v[160:163], v[94:97]
	v_mfma_f32_16x16x32_bf16 v[90:93], v[132:135], v[164:167], v[90:93]
	v_mfma_f32_16x16x32_bf16 v[86:89], v[132:135], v[168:171], v[86:89]
	v_mfma_f32_16x16x32_bf16 v[82:85], v[132:135], v[232:235], v[82:85]
	s_waitcnt lgkmcnt(3)
	v_mfma_f32_16x16x32_bf16 v[78:81], v[140:143], v[160:163], v[78:81]
	v_mfma_f32_16x16x32_bf16 v[74:77], v[140:143], v[164:167], v[74:77]
	v_mfma_f32_16x16x32_bf16 v[70:73], v[140:143], v[168:171], v[70:73]
	v_mfma_f32_16x16x32_bf16 v[66:69], v[140:143], v[232:235], v[66:69]
	s_waitcnt lgkmcnt(1)
	v_mfma_f32_16x16x32_bf16 v[62:65], v[144:147], v[160:163], v[62:65]
	v_mfma_f32_16x16x32_bf16 v[58:61], v[144:147], v[164:167], v[58:61]
	v_mfma_f32_16x16x32_bf16 v[54:57], v[144:147], v[168:171], v[54:57]
	v_mfma_f32_16x16x32_bf16 v[50:53], v[144:147], v[232:235], v[50:53]
	s_setprio 0
	s_waitcnt lgkmcnt(0)
	s_waitcnt vmcnt(0)
	s_add_i32 s13, s13, 0x10000
	s_addk_i32 s15, 0x80
	s_cmp_eq_u32 s15, 0x30400
	s_mov_b32 s2, 0x10000
	s_barrier
	s_cbranch_scc0 .Lrot3_top_l
	s_branch .Lrot3_top_n
.Lrot3_top_l:
	s_and_b32 s2, s13, 0x10000
	s_xor_b32 s10, s2, 0x10000
	s_add_i32 s16, s21, s10
	s_add_i32 s17, s15, 0xfffd0000
	s_add_i32 s30, s16, 0x8000
	s_mov_b32 s10, s66
	s_mov_b32 s11, s67
	v_add_u32_e32 v228, s2, v138
	v_add_u32_e32 v229, s2, v136
	ds_read_b128 v[132:135], v229 offset:0
	ds_read_b128 v[140:143], v229 offset:0x800
	ds_read_b128 v[144:147], v229 offset:0x1000
	ds_read_b128 v[148:151], v229 offset:0x1800
	ds_read_b128 v[152:155], v228 offset:0
	ds_read_b128 v[156:159], v228 offset:0x800
	s_setprio 1
	s_mov_b32 m0, s16
	s_nop 0
	buffer_load_dwordx4 v131, s[64:67], s17 offen lds
	s_mov_b32 m0, s30
	s_nop 0
	buffer_load_dwordx4 v131, s[8:11], s17 offen lds
	v_mfma_f32_16x16x32_bf16 v[46:49], v[236:239], v[160:163], v[46:49]
	v_mfma_f32_16x16x32_bf16 v[42:45], v[236:239], v[164:167], v[42:45]
	v_mfma_f32_16x16x32_bf16 v[38:41], v[236:239], v[168:171], v[38:41]
	v_mfma_f32_16x16x32_bf16 v[34:37], v[236:239], v[232:235], v[34:37]
	s_add_i32 m0, s16, 0x2000
	s_add_i32 s17, s15, 0xfffe0000
	buffer_load_dwordx4 v131, s[64:67], s17 offen lds
	v_mfma_f32_16x16x32_bf16 v[30:33], v[240:243], v[160:163], v[30:33]
	v_mfma_f32_16x16x32_bf16 v[26:29], v[240:243], v[164:167], v[26:29]
	v_mfma_f32_16x16x32_bf16 v[22:25], v[240:243], v[168:171], v[22:25]
	v_mfma_f32_16x16x32_bf16 v[18:21], v[240:243], v[232:235], v[18:21]
	s_add_i32 m0, s16, 0xa000
	s_nop 0
	buffer_load_dwordx4 v131, s[8:11], s17 offen lds
	v_mfma_f32_16x16x32_bf16 v[14:17], v[244:247], v[160:163], v[14:17]
	v_mfma_f32_16x16x32_bf16 v[10:13], v[244:247], v[164:167], v[10:13]
	v_mfma_f32_16x16x32_bf16 v[6:9], v[244:247], v[168:171], v[6:9]
	v_mfma_f32_16x16x32_bf16 v[2:5], v[244:247], v[232:235], v[2:5]
	s_add_i32 m0, s16, 0x4000
	s_add_i32 s17, s15, 0xffff0000
	buffer_load_dwordx4 v131, s[64:67], s17 offen lds
	ds_read_b128 v[160:163], v228 offset:0x1000
	v_xor_b32_e32 v176, 64, v228
.Lrot3_mid_l:
	s_waitcnt lgkmcnt(2)
	v_mfma_f32_16x16x32_bf16 v[126:129], v[152:155], v[132:135], v[126:129]
	v_mfma_f32_16x16x32_bf16 v[122:125], v[152:155], v[140:143], v[122:125]
	v_mfma_f32_16x16x32_bf16 v[118:121], v[152:155], v[144:147], v[118:121]
	v_mfma_f32_16x16x32_bf16 v[114:117], v[152:155], v[148:151], v[114:117]
	s_add_i32 m0, s16, 0xc000
	s_nop 0
	buffer_load_dwordx4 v131, s[8:11], s17 offen lds
	ds_read_b128 v[152:155], v228 offset:0x1800
	s_waitcnt lgkmcnt(2)
	v_mfma_f32_16x16x32_bf16 v[110:113], v[156:159], v[132:135], v[110:113]
	v_mfma_f32_16x16x32_bf16 v[106:109], v[156:159], v[140:143], v[106:109]
	v_mfma_f32_16x16x32_bf16 v[102:105], v[156:159], v[144:147], v[102:105]
	v_mfma_f32_16x16x32_bf16 v[98:101], v[156:159], v[148:151], v[98:101]
	s_add_i32 m0, s16, 0x6000
	s_nop 0
	buffer_load_dwordx4 v131, s[64:67], s15 offen lds
	ds_read_b128 v[156:159], v228 offset:0x2000
	s_waitcnt lgkmcnt(2)
	v_mfma_f32_16x16x32_bf16 v[94:97], v[160:163], v[132:135], v[94:97]
	v_mfma_f32_16x16x32_bf16 v[90:93], v[160:163], v[140:143], v[90:93]
	v_mfma_f32_16x16x32_bf16 v[86:89], v[160:163], v[144:147], v[86:89]
	v_mfma_f32_16x16x32_bf16 v[82:85], v[160:163], v[148:151], v[82:85]
	s_add_i32 m0, s16, 0xe000
	s_nop 0
	buffer_load_dwordx4 v131, s[8:11], s15 offen lds
	ds_read_b128 v[160:163], v228 offset:0x2800
	s_waitcnt lgkmcnt(2)
	v_mfma_f32_16x16x32_bf16 v[78:81], v[152:155], v[132:135], v[78:81]
	v_mfma_f32_16x16x32_bf16 v[74:77], v[152:155], v[140:143], v[74:77]
	v_mfma_f32_16x16x32_bf16 v[70:73], v[152:155], v[144:147], v[70:73]
	v_mfma_f32_16x16x32_bf16 v[66:69], v[152:155], v[148:151], v[66:69]
	ds_read_b128 v[152:155], v228 offset:0x3000
	s_waitcnt lgkmcnt(2)
	v_mfma_f32_16x16x32_bf16 v[62:65], v[156:159], v[132:135], v[62:65]
	v_mfma_f32_16x16x32_bf16 v[58:61], v[156:159], v[140:143], v[58:61]
	v_mfma_f32_16x16x32_bf16 v[54:57], v[156:159], v[144:147], v[54:57]
	v_mfma_f32_16x16x32_bf16 v[50:53], v[156:159], v[148:151], v[50:53]
	ds_read_b128 v[156:159], v228 offset:0x3800
	s_waitcnt lgkmcnt(2)
	v_xor_b32_e32 v0, 64, v229
	v_mfma_f32_16x16x32_bf16 v[46:49], v[160:163], v[132:135], v[46:49]
	v_mfma_f32_16x16x32_bf16 v[42:45], v[160:163], v[140:143], v[42:45]
	v_mfma_f32_16x16x32_bf16 v[38:41], v[160:163], v[144:147], v[38:41]
	v_mfma_f32_16x16x32_bf16 v[34:37], v[160:163], v[148:151], v[34:37]
	ds_read_b128 v[160:163], v0 offset:0
	ds_read_b128 v[164:167], v0 offset:0x800
	ds_read_b128 v[168:171], v0 offset:0x1000
	s_waitcnt lgkmcnt(4)
	v_mfma_f32_16x16x32_bf16 v[30:33], v[152:155], v[132:135], v[30:33]
	v_mfma_f32_16x16x32_bf16 v[26:29], v[152:155], v[140:143], v[26:29]
	v_mfma_f32_16x16x32_bf16 v[22:25], v[152:155], v[144:147], v[22:25]
	v_mfma_f32_16x16x32_bf16 v[18:21], v[152:155], v[148:151], v[18:21]
	ds_read_b128 v[232:235], v0 offset:0x1800
	ds_read_b128 v[172:175], v176 offset:0
	ds_read_b128 v[202:205], v176 offset:0x800
	s_waitcnt lgkmcnt(6)
	v_mfma_f32_16x16x32_bf16 v[14:17], v[156:159], v[132:135], v[14:17]
	v_mfma_f32_16x16x32_bf16 v[10:13], v[156:159], v[140:143], v[10:13]
	v_mfma_f32_16x16x32_bf16 v[6:9], v[156:159], v[144:147], v[6:9]
	v_mfma_f32_16x16x32_bf16 v[2:5], v[156:159], v[148:151], v[2:5]
	ds_read_b128 v[132:135], v176 offset:0x1000
	ds_read_b128 v[236:239], v176 offset:0x2800
	s_waitcnt lgkmcnt(3)
	v_mfma_f32_16x16x32_bf16 v[126:129], v[172:175], v[160:163], v[126:129]
	v_mfma_f32_16x16x32_bf16 v[122:125], v[172:175], v[164:167], v[122:125]
	v_mfma_f32_16x16x32_bf16 v[118:121], v[172:175], v[168:171], v[118:121]
	v_mfma_f32_16x16x32_bf16 v[114:117], v[172:175], v[232:235], v[114:117]
	ds_read_b128 v[140:143], v176 offset:0x1800
	ds_read_b128 v[240:243], v176 offset:0x3000
	s_waitcnt lgkmcnt(4)
	v_mfma_f32_16x16x32_bf16 v[110:113], v[202:205], v[160:163], v[110:113]
	v_mfma_f32_16x16x32_bf16 v[106:109], v[202:205], v[164:167], v[106:109]
	v_mfma_f32_16x16x32_bf16 v[102:105], v[202:205], v[168:171], v[102:105]
	v_mfma_f32_16x16x32_bf16 v[98:101], v[202:205], v[232:235], v[98:101]
	ds_read_b128 v[144:147], v176 offset:0x2000
	ds_read_b128 v[244:247], v176 offset:0x3800
	s_waitcnt lgkmcnt(5)
	v_mfma_f32_16x16x32_bf16 v[94:97], v[132:135], v[160:163], v[94:97]
	v_mfma_f32_16x16x32_bf16 v[90:93], v[132:135], v[164:167], v[90:93]
	v_mfma_f32_16x16x32_bf16 v[86:89], v[132:135], v[168:171], v[86:89]
	v_mfma_f32_16x16x32_bf16 v[82:85], v[132:135], v[232:235], v[82:85]
	s_waitcnt lgkmcnt(3)
	v_mfma_f32_16x16x32_bf16 v[78:81], v[140:143], v[160:163], v[78:81]
	v_mfma_f32_16x16x32_bf16 v[74:77], v[140:143], v[164:167], v[74:77]
	v_mfma_f32_16x16x32_bf16 v[70:73], v[140:143], v[168:171], v[70:73]
	v_mfma_f32_16x16x32_bf16 v[66:69], v[140:143], v[232:235], v[66:69]
	s_waitcnt lgkmcnt(1)
	v_mfma_f32_16x16x32_bf16 v[62:65], v[144:147], v[160:163], v[62:65]
	v_mfma_f32_16x16x32_bf16 v[58:61], v[144:147], v[164:167], v[58:61]
	v_mfma_f32_16x16x32_bf16 v[54:57], v[144:147], v[168:171], v[54:57]
	v_mfma_f32_16x16x32_bf16 v[50:53], v[144:147], v[232:235], v[50:53]
	s_setprio 0
	s_waitcnt lgkmcnt(0)
	s_waitcnt vmcnt(0)
	s_add_i32 s13, s13, 0x10000
	s_addk_i32 s15, 0x80
	s_cmp_eq_u32 s15, 0x30400
	s_mov_b32 s2, 0x10000
	s_barrier
	s_cbranch_scc0 .Lrot3_top_l

.LBB0_271:
	s_cmp_eq_u32 s21, 0x60800
	s_mov_b32 s2, 0x10000
	s_and_b32 s2, s19, 0x10000
	s_xor_b32 s10, s2, 0x10000
	s_add_i32 s51, s29, s10
	s_add_i32 s52, s21, 0xfffa0000
	s_add_i32 s53, s51, 0x8000
	s_mov_b32 s10, s66
	s_mov_b32 s11, s67
	s_waitcnt lgkmcnt(0)
	v_add_u32_e32 v228, s2, v205
	v_add_u32_e32 v229, s2, v202
	ds_read_b128 v[130:133], v229 offset:0
	ds_read_b128 v[134:137], v229 offset:0x800
	ds_read_b128 v[138:141], v229 offset:0x1000
	ds_read_b128 v[142:145], v229 offset:0x1800
	ds_read_b128 v[146:149], v228 offset:0
	ds_read_b128 v[150:153], v228 offset:0x800
	s_setprio 1
	s_mov_b32 m0, s51
	s_nop 0
	buffer_load_dwordx4 v173, s[64:67], s52 offen lds
	s_mov_b32 m0, s53
	s_nop 0
	buffer_load_dwordx4 v248, s[8:11], s52 offen lds
	s_add_i32 m0, s51, 0x2000
	s_add_i32 s52, s21, 0xfffc0000
	buffer_load_dwordx4 v173, s[64:67], s52 offen lds
	s_add_i32 m0, s51, 0xa000
	s_nop 0
	buffer_load_dwordx4 v248, s[8:11], s52 offen lds
	s_add_i32 m0, s51, 0x4000
	s_add_i32 s52, s21, 0xfffe0000
	buffer_load_dwordx4 v173, s[64:67], s52 offen lds
	ds_read_b128 v[154:157], v228 offset:0x1000
	v_xor_b32_e32 v177, 64, v228
	s_waitcnt lgkmcnt(2)
	v_mfma_f32_16x16x32_bf16 v[122:125], v[146:149], v[130:133], 0
	v_mfma_f32_16x16x32_bf16 v[126:129], v[146:149], v[134:137], 0
	v_mfma_f32_16x16x32_bf16 v[118:121], v[146:149], v[138:141], 0
	v_mfma_f32_16x16x32_bf16 v[114:117], v[146:149], v[142:145], 0
	s_add_i32 m0, s51, 0xc000
	s_nop 0
	buffer_load_dwordx4 v248, s[8:11], s52 offen lds
	ds_read_b128 v[146:149], v228 offset:0x1800
	s_waitcnt lgkmcnt(2)
	v_mfma_f32_16x16x32_bf16 v[110:113], v[150:153], v[130:133], 0
	v_mfma_f32_16x16x32_bf16 v[106:109], v[150:153], v[134:137], 0
	v_mfma_f32_16x16x32_bf16 v[102:105], v[150:153], v[138:141], 0
	v_mfma_f32_16x16x32_bf16 v[98:101], v[150:153], v[142:145], 0
	s_add_i32 m0, s51, 0x6000
	s_nop 0
	buffer_load_dwordx4 v173, s[64:67], s21 offen lds
	ds_read_b128 v[150:153], v228 offset:0x2000
	s_waitcnt lgkmcnt(2)
	v_mfma_f32_16x16x32_bf16 v[94:97], v[154:157], v[130:133], 0
	v_mfma_f32_16x16x32_bf16 v[90:93], v[154:157], v[134:137], 0
	v_mfma_f32_16x16x32_bf16 v[86:89], v[154:157], v[138:141], 0
	v_mfma_f32_16x16x32_bf16 v[82:85], v[154:157], v[142:145], 0
	s_add_i32 m0, s51, 0xe000
	s_nop 0
	buffer_load_dwordx4 v248, s[8:11], s21 offen lds
	ds_read_b128 v[154:157], v228 offset:0x2800
	s_waitcnt lgkmcnt(2)
	v_mfma_f32_16x16x32_bf16 v[78:81], v[146:149], v[130:133], 0
	v_mfma_f32_16x16x32_bf16 v[74:77], v[146:149], v[134:137], 0
	v_mfma_f32_16x16x32_bf16 v[70:73], v[146:149], v[138:141], 0
	v_mfma_f32_16x16x32_bf16 v[66:69], v[146:149], v[142:145], 0
	ds_read_b128 v[146:149], v228 offset:0x3000
	s_waitcnt lgkmcnt(2)
	v_mfma_f32_16x16x32_bf16 v[62:65], v[150:153], v[130:133], 0
	v_mfma_f32_16x16x32_bf16 v[58:61], v[150:153], v[134:137], 0
	v_mfma_f32_16x16x32_bf16 v[54:57], v[150:153], v[138:141], 0
	v_mfma_f32_16x16x32_bf16 v[50:53], v[150:153], v[142:145], 0
	ds_read_b128 v[150:153], v228 offset:0x3800
	s_waitcnt lgkmcnt(2)
	v_xor_b32_e32 v0, 64, v229
	v_mfma_f32_16x16x32_bf16 v[46:49], v[154:157], v[130:133], 0
	v_mfma_f32_16x16x32_bf16 v[42:45], v[154:157], v[134:137], 0
	v_mfma_f32_16x16x32_bf16 v[38:41], v[154:157], v[138:141], 0
	v_mfma_f32_16x16x32_bf16 v[34:37], v[154:157], v[142:145], 0
	ds_read_b128 v[154:157], v0 offset:0
	ds_read_b128 v[158:161], v0 offset:0x800
	ds_read_b128 v[162:165], v0 offset:0x1000
	s_waitcnt lgkmcnt(4)
	v_mfma_f32_16x16x32_bf16 v[30:33], v[146:149], v[130:133], 0
	v_mfma_f32_16x16x32_bf16 v[26:29], v[146:149], v[134:137], 0
	v_mfma_f32_16x16x32_bf16 v[22:25], v[146:149], v[138:141], 0
	v_mfma_f32_16x16x32_bf16 v[18:21], v[146:149], v[142:145], 0
	ds_read_b128 v[232:235], v0 offset:0x1800
	ds_read_b128 v[166:169], v177 offset:0
	ds_read_b128 v[206:209], v177 offset:0x800
	s_waitcnt lgkmcnt(6)
	v_mfma_f32_16x16x32_bf16 v[14:17], v[150:153], v[130:133], 0
	v_mfma_f32_16x16x32_bf16 v[10:13], v[150:153], v[134:137], 0
	v_mfma_f32_16x16x32_bf16 v[6:9], v[150:153], v[138:141], 0
	v_mfma_f32_16x16x32_bf16 v[2:5], v[150:153], v[142:145], 0
	ds_read_b128 v[130:133], v177 offset:0x1000
	ds_read_b128 v[236:239], v177 offset:0x2800
	s_waitcnt lgkmcnt(3)
	v_mfma_f32_16x16x32_bf16 v[122:125], v[166:169], v[154:157], v[122:125]
	v_mfma_f32_16x16x32_bf16 v[126:129], v[166:169], v[158:161], v[126:129]
	v_mfma_f32_16x16x32_bf16 v[118:121], v[166:169], v[162:165], v[118:121]
	v_mfma_f32_16x16x32_bf16 v[114:117], v[166:169], v[232:235], v[114:117]
	ds_read_b128 v[134:137], v177 offset:0x1800
	ds_read_b128 v[240:243], v177 offset:0x3000
	s_waitcnt lgkmcnt(4)
	v_mfma_f32_16x16x32_bf16 v[110:113], v[206:209], v[154:157], v[110:113]
	v_mfma_f32_16x16x32_bf16 v[106:109], v[206:209], v[158:161], v[106:109]
	v_mfma_f32_16x16x32_bf16 v[102:105], v[206:209], v[162:165], v[102:105]
	v_mfma_f32_16x16x32_bf16 v[98:101], v[206:209], v[232:235], v[98:101]
	ds_read_b128 v[138:141], v177 offset:0x2000
	ds_read_b128 v[244:247], v177 offset:0x3800
	s_waitcnt lgkmcnt(5)
	v_mfma_f32_16x16x32_bf16 v[94:97], v[130:133], v[154:157], v[94:97]
	v_mfma_f32_16x16x32_bf16 v[90:93], v[130:133], v[158:161], v[90:93]
	v_mfma_f32_16x16x32_bf16 v[86:89], v[130:133], v[162:165], v[86:89]
	v_mfma_f32_16x16x32_bf16 v[82:85], v[130:133], v[232:235], v[82:85]
	s_waitcnt lgkmcnt(3)
	v_mfma_f32_16x16x32_bf16 v[78:81], v[134:137], v[154:157], v[78:81]
	v_mfma_f32_16x16x32_bf16 v[74:77], v[134:137], v[158:161], v[74:77]
	v_mfma_f32_16x16x32_bf16 v[70:73], v[134:137], v[162:165], v[70:73]
	v_mfma_f32_16x16x32_bf16 v[66:69], v[134:137], v[232:235], v[66:69]
	s_waitcnt lgkmcnt(1)
	v_mfma_f32_16x16x32_bf16 v[62:65], v[138:141], v[154:157], v[62:65]
	v_mfma_f32_16x16x32_bf16 v[58:61], v[138:141], v[158:161], v[58:61]
	v_mfma_f32_16x16x32_bf16 v[54:57], v[138:141], v[162:165], v[54:57]
	v_mfma_f32_16x16x32_bf16 v[50:53], v[138:141], v[232:235], v[50:53]
	s_setprio 0
	s_waitcnt lgkmcnt(0)
	s_waitcnt vmcnt(0)
	s_add_i32 s19, s19, 0x10000
	s_addk_i32 s21, 0x80
	s_cmp_eq_u32 s21, 0x60800
	s_mov_b32 s2, 0x10000
	s_barrier
	s_cbranch_scc0 .Lrot2_top_l
	s_branch .Lrot2_top_n
.Lrot2_top_l:
	s_and_b32 s2, s19, 0x10000
	s_xor_b32 s10, s2, 0x10000
	s_add_i32 s51, s29, s10
	s_add_i32 s52, s21, 0xfffa0000
	s_add_i32 s53, s51, 0x8000
	s_mov_b32 s10, s66
	s_mov_b32 s11, s67
	v_add_u32_e32 v228, s2, v205
	v_add_u32_e32 v229, s2, v202
	ds_read_b128 v[130:133], v229 offset:0
	ds_read_b128 v[134:137], v229 offset:0x800
	ds_read_b128 v[138:141], v229 offset:0x1000
	ds_read_b128 v[142:145], v229 offset:0x1800
	ds_read_b128 v[146:149], v228 offset:0
	ds_read_b128 v[150:153], v228 offset:0x800
	s_setprio 1
	s_mov_b32 m0, s51
	s_nop 0
	buffer_load_dwordx4 v173, s[64:67], s52 offen lds
	s_mov_b32 m0, s53
	s_nop 0
	buffer_load_dwordx4 v248, s[8:11], s52 offen lds
	v_mfma_f32_16x16x32_bf16 v[46:49], v[236:239], v[154:157], v[46:49]
	v_mfma_f32_16x16x32_bf16 v[42:45], v[236:239], v[158:161], v[42:45]
	v_mfma_f32_16x16x32_bf16 v[38:41], v[236:239], v[162:165], v[38:41]
	v_mfma_f32_16x16x32_bf16 v[34:37], v[236:239], v[232:235], v[34:37]
	s_add_i32 m0, s51, 0x2000
	s_add_i32 s52, s21, 0xfffc0000
	buffer_load_dwordx4 v173, s[64:67], s52 offen lds
	v_mfma_f32_16x16x32_bf16 v[30:33], v[240:243], v[154:157], v[30:33]
	v_mfma_f32_16x16x32_bf16 v[26:29], v[240:243], v[158:161], v[26:29]
	v_mfma_f32_16x16x32_bf16 v[22:25], v[240:243], v[162:165], v[22:25]
	v_mfma_f32_16x16x32_bf16 v[18:21], v[240:243], v[232:235], v[18:21]
	s_add_i32 m0, s51, 0xa000
	s_nop 0
	buffer_load_dwordx4 v248, s[8:11], s52 offen lds
	v_mfma_f32_16x16x32_bf16 v[14:17], v[244:247], v[154:157], v[14:17]
	v_mfma_f32_16x16x32_bf16 v[10:13], v[244:247], v[158:161], v[10:13]
	v_mfma_f32_16x16x32_bf16 v[6:9], v[244:247], v[162:165], v[6:9]
	v_mfma_f32_16x16x32_bf16 v[2:5], v[244:247], v[232:235], v[2:5]
	s_add_i32 m0, s51, 0x4000
	s_add_i32 s52, s21, 0xfffe0000
	buffer_load_dwordx4 v173, s[64:67], s52 offen lds
	ds_read_b128 v[154:157], v228 offset:0x1000
	v_xor_b32_e32 v177, 64, v228
.Lrot2_mid_l:
	s_waitcnt lgkmcnt(2)
	v_mfma_f32_16x16x32_bf16 v[122:125], v[146:149], v[130:133], v[122:125]
	v_mfma_f32_16x16x32_bf16 v[126:129], v[146:149], v[134:137], v[126:129]
	v_mfma_f32_16x16x32_bf16 v[118:121], v[146:149], v[138:141], v[118:121]
	v_mfma_f32_16x16x32_bf16 v[114:117], v[146:149], v[142:145], v[114:117]
	s_add_i32 m0, s51, 0xc000
	s_nop 0
	buffer_load_dwordx4 v248, s[8:11], s52 offen lds
	ds_read_b128 v[146:149], v228 offset:0x1800
	s_waitcnt lgkmcnt(2)
	v_mfma_f32_16x16x32_bf16 v[110:113], v[150:153], v[130:133], v[110:113]
	v_mfma_f32_16x16x32_bf16 v[106:109], v[150:153], v[134:137], v[106:109]
	v_mfma_f32_16x16x32_bf16 v[102:105], v[150:153], v[138:141], v[102:105]
	v_mfma_f32_16x16x32_bf16 v[98:101], v[150:153], v[142:145], v[98:101]
	s_add_i32 m0, s51, 0x6000
	s_nop 0
	buffer_load_dwordx4 v173, s[64:67], s21 offen lds
	ds_read_b128 v[150:153], v228 offset:0x2000
	s_waitcnt lgkmcnt(2)
	v_mfma_f32_16x16x32_bf16 v[94:97], v[154:157], v[130:133], v[94:97]
	v_mfma_f32_16x16x32_bf16 v[90:93], v[154:157], v[134:137], v[90:93]
	v_mfma_f32_16x16x32_bf16 v[86:89], v[154:157], v[138:141], v[86:89]
	v_mfma_f32_16x16x32_bf16 v[82:85], v[154:157], v[142:145], v[82:85]
	s_add_i32 m0, s51, 0xe000
	s_nop 0
	buffer_load_dwordx4 v248, s[8:11], s21 offen lds
	ds_read_b128 v[154:157], v228 offset:0x2800
	s_waitcnt lgkmcnt(2)
	v_mfma_f32_16x16x32_bf16 v[78:81], v[146:149], v[130:133], v[78:81]
	v_mfma_f32_16x16x32_bf16 v[74:77], v[146:149], v[134:137], v[74:77]
	v_mfma_f32_16x16x32_bf16 v[70:73], v[146:149], v[138:141], v[70:73]
	v_mfma_f32_16x16x32_bf16 v[66:69], v[146:149], v[142:145], v[66:69]
	ds_read_b128 v[146:149], v228 offset:0x3000
	s_waitcnt lgkmcnt(2)
	v_mfma_f32_16x16x32_bf16 v[62:65], v[150:153], v[130:133], v[62:65]
	v_mfma_f32_16x16x32_bf16 v[58:61], v[150:153], v[134:137], v[58:61]
	v_mfma_f32_16x16x32_bf16 v[54:57], v[150:153], v[138:141], v[54:57]
	v_mfma_f32_16x16x32_bf16 v[50:53], v[150:153], v[142:145], v[50:53]
	ds_read_b128 v[150:153], v228 offset:0x3800
	s_waitcnt lgkmcnt(2)
	v_xor_b32_e32 v0, 64, v229
	v_mfma_f32_16x16x32_bf16 v[46:49], v[154:157], v[130:133], v[46:49]
	v_mfma_f32_16x16x32_bf16 v[42:45], v[154:157], v[134:137], v[42:45]
	v_mfma_f32_16x16x32_bf16 v[38:41], v[154:157], v[138:141], v[38:41]
	v_mfma_f32_16x16x32_bf16 v[34:37], v[154:157], v[142:145], v[34:37]
	ds_read_b128 v[154:157], v0 offset:0
	ds_read_b128 v[158:161], v0 offset:0x800
	ds_read_b128 v[162:165], v0 offset:0x1000
	s_waitcnt lgkmcnt(4)
	v_mfma_f32_16x16x32_bf16 v[30:33], v[146:149], v[130:133], v[30:33]
	v_mfma_f32_16x16x32_bf16 v[26:29], v[146:149], v[134:137], v[26:29]
	v_mfma_f32_16x16x32_bf16 v[22:25], v[146:149], v[138:141], v[22:25]
	v_mfma_f32_16x16x32_bf16 v[18:21], v[146:149], v[142:145], v[18:21]
	ds_read_b128 v[232:235], v0 offset:0x1800
	ds_read_b128 v[166:169], v177 offset:0
	ds_read_b128 v[206:209], v177 offset:0x800
	s_waitcnt lgkmcnt(6)
	v_mfma_f32_16x16x32_bf16 v[14:17], v[150:153], v[130:133], v[14:17]
	v_mfma_f32_16x16x32_bf16 v[10:13], v[150:153], v[134:137], v[10:13]
	v_mfma_f32_16x16x32_bf16 v[6:9], v[150:153], v[138:141], v[6:9]
	v_mfma_f32_16x16x32_bf16 v[2:5], v[150:153], v[142:145], v[2:5]
	ds_read_b128 v[130:133], v177 offset:0x1000
	ds_read_b128 v[236:239], v177 offset:0x2800
	s_waitcnt lgkmcnt(3)
	v_mfma_f32_16x16x32_bf16 v[122:125], v[166:169], v[154:157], v[122:125]
	v_mfma_f32_16x16x32_bf16 v[126:129], v[166:169], v[158:161], v[126:129]
	v_mfma_f32_16x16x32_bf16 v[118:121], v[166:169], v[162:165], v[118:121]
	v_mfma_f32_16x16x32_bf16 v[114:117], v[166:169], v[232:235], v[114:117]
	ds_read_b128 v[134:137], v177 offset:0x1800
	ds_read_b128 v[240:243], v177 offset:0x3000
	s_waitcnt lgkmcnt(4)
	v_mfma_f32_16x16x32_bf16 v[110:113], v[206:209], v[154:157], v[110:113]
	v_mfma_f32_16x16x32_bf16 v[106:109], v[206:209], v[158:161], v[106:109]
	v_mfma_f32_16x16x32_bf16 v[102:105], v[206:209], v[162:165], v[102:105]
	v_mfma_f32_16x16x32_bf16 v[98:101], v[206:209], v[232:235], v[98:101]
	ds_read_b128 v[138:141], v177 offset:0x2000
	ds_read_b128 v[244:247], v177 offset:0x3800
	s_waitcnt lgkmcnt(5)
	v_mfma_f32_16x16x32_bf16 v[94:97], v[130:133], v[154:157], v[94:97]
	v_mfma_f32_16x16x32_bf16 v[90:93], v[130:133], v[158:161], v[90:93]
	v_mfma_f32_16x16x32_bf16 v[86:89], v[130:133], v[162:165], v[86:89]
	v_mfma_f32_16x16x32_bf16 v[82:85], v[130:133], v[232:235], v[82:85]
	s_waitcnt lgkmcnt(3)
	v_mfma_f32_16x16x32_bf16 v[78:81], v[134:137], v[154:157], v[78:81]
	v_mfma_f32_16x16x32_bf16 v[74:77], v[134:137], v[158:161], v[74:77]
	v_mfma_f32_16x16x32_bf16 v[70:73], v[134:137], v[162:165], v[70:73]
	v_mfma_f32_16x16x32_bf16 v[66:69], v[134:137], v[232:235], v[66:69]
	s_waitcnt lgkmcnt(1)
	v_mfma_f32_16x16x32_bf16 v[62:65], v[138:141], v[154:157], v[62:65]
	v_mfma_f32_16x16x32_bf16 v[58:61], v[138:141], v[158:161], v[58:61]
	v_mfma_f32_16x16x32_bf16 v[54:57], v[138:141], v[162:165], v[54:57]
	v_mfma_f32_16x16x32_bf16 v[50:53], v[138:141], v[232:235], v[50:53]
	s_setprio 0
	s_waitcnt lgkmcnt(0)
	s_waitcnt vmcnt(0)
	s_add_i32 s19, s19, 0x10000
	s_addk_i32 s21, 0x80
	s_cmp_eq_u32 s21, 0x60800
	s_mov_b32 s2, 0x10000
	s_barrier
	s_cbranch_scc0 .Lrot2_top_l

.LBB0_296:
	s_and_b32 s2, s44, 0x10000
	s_cmp_ge_u32 s41, s24
	s_xor_b32 s14, s2, 0x10000
	s_add_i32 s46, s26, s14
	s_add_i32 s47, s46, 0x8000
	s_mov_b32 s14, s66
	s_mov_b32 s15, s67
	s_waitcnt lgkmcnt(0)
	v_add_u32_e32 v228, s2, v143
	v_add_u32_e32 v229, s2, v133
	ds_read_b128 v[134:137], v229 offset:0
	ds_read_b128 v[138:141], v229 offset:0x800
	ds_read_b128 v[144:147], v229 offset:0x1000
	ds_read_b128 v[148:151], v229 offset:0x1800
	ds_read_b128 v[152:155], v228 offset:0
	ds_read_b128 v[156:159], v228 offset:0x800
	s_setprio 1
	s_mov_b32 m0, s46
	s_nop 0
	buffer_load_dwordx4 v131, s[64:67], s45 offen lds
	s_mov_b32 m0, s47
	s_add_i32 s47, s27, s45
	buffer_load_dwordx4 v248, s[12:15], s45 offen lds
	s_add_i32 m0, s46, 0x2000
	s_nop 0
	buffer_load_dwordx4 v131, s[64:67], s47 offen lds
	s_add_i32 m0, s46, 0xa000
	s_nop 0
	buffer_load_dwordx4 v248, s[12:15], s47 offen lds
	s_add_i32 m0, s46, 0x4000
	s_add_i32 s47, s34, s45
	buffer_load_dwordx4 v131, s[64:67], s47 offen lds
	ds_read_b128 v[160:163], v228 offset:0x1000
	v_xor_b32_e32 v176, 64, v228
	s_waitcnt lgkmcnt(2)
	v_mfma_f32_16x16x32_bf16 v[126:129], v[152:155], v[134:137], 0
	v_mfma_f32_16x16x32_bf16 v[122:125], v[152:155], v[138:141], 0
	v_mfma_f32_16x16x32_bf16 v[118:121], v[152:155], v[144:147], 0
	v_mfma_f32_16x16x32_bf16 v[114:117], v[152:155], v[148:151], 0
	s_add_i32 m0, s46, 0xc000
	s_nop 0
	buffer_load_dwordx4 v248, s[12:15], s47 offen lds
	ds_read_b128 v[152:155], v228 offset:0x1800
	s_waitcnt lgkmcnt(2)
	v_mfma_f32_16x16x32_bf16 v[110:113], v[156:159], v[134:137], 0
	v_mfma_f32_16x16x32_bf16 v[106:109], v[156:159], v[138:141], 0
	v_mfma_f32_16x16x32_bf16 v[102:105], v[156:159], v[144:147], 0
	v_mfma_f32_16x16x32_bf16 v[98:101], v[156:159], v[148:151], 0
	s_add_i32 m0, s46, 0x6000
	s_add_i32 s47, s37, s45
	buffer_load_dwordx4 v131, s[64:67], s47 offen lds
	ds_read_b128 v[156:159], v228 offset:0x2000
	s_waitcnt lgkmcnt(2)
	v_mfma_f32_16x16x32_bf16 v[94:97], v[160:163], v[134:137], 0
	v_mfma_f32_16x16x32_bf16 v[90:93], v[160:163], v[138:141], 0
	v_mfma_f32_16x16x32_bf16 v[86:89], v[160:163], v[144:147], 0
	v_mfma_f32_16x16x32_bf16 v[82:85], v[160:163], v[148:151], 0
	s_add_i32 m0, s46, 0xe000
	s_nop 0
	buffer_load_dwordx4 v248, s[12:15], s47 offen lds
	ds_read_b128 v[160:163], v228 offset:0x2800
	s_waitcnt lgkmcnt(2)
	v_mfma_f32_16x16x32_bf16 v[78:81], v[152:155], v[134:137], 0
	v_mfma_f32_16x16x32_bf16 v[74:77], v[152:155], v[138:141], 0
	v_mfma_f32_16x16x32_bf16 v[70:73], v[152:155], v[144:147], 0
	v_mfma_f32_16x16x32_bf16 v[66:69], v[152:155], v[148:151], 0
	ds_read_b128 v[152:155], v228 offset:0x3000
	s_waitcnt lgkmcnt(2)
	v_mfma_f32_16x16x32_bf16 v[62:65], v[156:159], v[134:137], 0
	v_mfma_f32_16x16x32_bf16 v[58:61], v[156:159], v[138:141], 0
	v_mfma_f32_16x16x32_bf16 v[54:57], v[156:159], v[144:147], 0
	v_mfma_f32_16x16x32_bf16 v[50:53], v[156:159], v[148:151], 0
	ds_read_b128 v[156:159], v228 offset:0x3800
	s_waitcnt lgkmcnt(2)
	v_xor_b32_e32 v0, 64, v229
	v_mfma_f32_16x16x32_bf16 v[46:49], v[160:163], v[134:137], 0
	v_mfma_f32_16x16x32_bf16 v[42:45], v[160:163], v[138:141], 0
	v_mfma_f32_16x16x32_bf16 v[38:41], v[160:163], v[144:147], 0
	v_mfma_f32_16x16x32_bf16 v[34:37], v[160:163], v[148:151], 0
	ds_read_b128 v[160:163], v0 offset:0
	ds_read_b128 v[164:167], v0 offset:0x800
	ds_read_b128 v[168:171], v0 offset:0x1000
	s_waitcnt lgkmcnt(4)
	v_mfma_f32_16x16x32_bf16 v[30:33], v[152:155], v[134:137], 0
	v_mfma_f32_16x16x32_bf16 v[26:29], v[152:155], v[138:141], 0
	v_mfma_f32_16x16x32_bf16 v[22:25], v[152:155], v[144:147], 0
	v_mfma_f32_16x16x32_bf16 v[18:21], v[152:155], v[148:151], 0
	ds_read_b128 v[232:235], v0 offset:0x1800
	ds_read_b128 v[172:175], v176 offset:0
	ds_read_b128 v[202:205], v176 offset:0x800
	s_waitcnt lgkmcnt(6)
	v_mfma_f32_16x16x32_bf16 v[14:17], v[156:159], v[134:137], 0
	v_mfma_f32_16x16x32_bf16 v[10:13], v[156:159], v[138:141], 0
	v_mfma_f32_16x16x32_bf16 v[6:9], v[156:159], v[144:147], 0
	v_mfma_f32_16x16x32_bf16 v[2:5], v[156:159], v[148:151], 0
	ds_read_b128 v[134:137], v176 offset:0x1000
	ds_read_b128 v[236:239], v176 offset:0x2800
	s_waitcnt lgkmcnt(3)
	v_mfma_f32_16x16x32_bf16 v[126:129], v[172:175], v[160:163], v[126:129]
	v_mfma_f32_16x16x32_bf16 v[122:125], v[172:175], v[164:167], v[122:125]
	v_mfma_f32_16x16x32_bf16 v[118:121], v[172:175], v[168:171], v[118:121]
	v_mfma_f32_16x16x32_bf16 v[114:117], v[172:175], v[232:235], v[114:117]
	ds_read_b128 v[138:141], v176 offset:0x1800
	ds_read_b128 v[240:243], v176 offset:0x3000
	s_waitcnt lgkmcnt(4)
	v_mfma_f32_16x16x32_bf16 v[110:113], v[202:205], v[160:163], v[110:113]
	v_mfma_f32_16x16x32_bf16 v[106:109], v[202:205], v[164:167], v[106:109]
	v_mfma_f32_16x16x32_bf16 v[102:105], v[202:205], v[168:171], v[102:105]
	v_mfma_f32_16x16x32_bf16 v[98:101], v[202:205], v[232:235], v[98:101]
	ds_read_b128 v[144:147], v176 offset:0x2000
	ds_read_b128 v[244:247], v176 offset:0x3800
	s_waitcnt lgkmcnt(5)
	v_mfma_f32_16x16x32_bf16 v[94:97], v[134:137], v[160:163], v[94:97]
	v_mfma_f32_16x16x32_bf16 v[90:93], v[134:137], v[164:167], v[90:93]
	v_mfma_f32_16x16x32_bf16 v[86:89], v[134:137], v[168:171], v[86:89]
	v_mfma_f32_16x16x32_bf16 v[82:85], v[134:137], v[232:235], v[82:85]
	s_waitcnt lgkmcnt(3)
	v_mfma_f32_16x16x32_bf16 v[78:81], v[138:141], v[160:163], v[78:81]
	v_mfma_f32_16x16x32_bf16 v[74:77], v[138:141], v[164:167], v[74:77]
	v_mfma_f32_16x16x32_bf16 v[70:73], v[138:141], v[168:171], v[70:73]
	v_mfma_f32_16x16x32_bf16 v[66:69], v[138:141], v[232:235], v[66:69]
	s_waitcnt lgkmcnt(1)
	v_mfma_f32_16x16x32_bf16 v[62:65], v[144:147], v[160:163], v[62:65]
	v_mfma_f32_16x16x32_bf16 v[58:61], v[144:147], v[164:167], v[58:61]
	v_mfma_f32_16x16x32_bf16 v[54:57], v[144:147], v[168:171], v[54:57]
	v_mfma_f32_16x16x32_bf16 v[50:53], v[144:147], v[232:235], v[50:53]
	s_setprio 0
	s_waitcnt lgkmcnt(0)
	s_waitcnt vmcnt(0)
	s_add_i32 s44, s44, 0x10000
	s_addk_i32 s45, 0x80
	s_add_i32 s41, s41, 1
	s_and_b32 s2, s44, 0x10000
	s_cmp_ge_u32 s41, s24
	s_barrier
	s_cbranch_scc0 .Lrot1_top_l
	s_branch .Lrot1_top_n
.Lrot1_top_l:
	s_xor_b32 s14, s2, 0x10000
	s_add_i32 s46, s26, s14
	s_add_i32 s47, s46, 0x8000
	s_mov_b32 s14, s66
	s_mov_b32 s15, s67
	v_add_u32_e32 v228, s2, v143
	v_add_u32_e32 v229, s2, v133
	ds_read_b128 v[134:137], v229 offset:0
	ds_read_b128 v[138:141], v229 offset:0x800
	ds_read_b128 v[144:147], v229 offset:0x1000
	ds_read_b128 v[148:151], v229 offset:0x1800
	ds_read_b128 v[152:155], v228 offset:0
	ds_read_b128 v[156:159], v228 offset:0x800
	s_setprio 1
	s_mov_b32 m0, s46
	s_nop 0
	buffer_load_dwordx4 v131, s[64:67], s45 offen lds
	s_mov_b32 m0, s47
	s_add_i32 s47, s27, s45
	buffer_load_dwordx4 v248, s[12:15], s45 offen lds
	v_mfma_f32_16x16x32_bf16 v[46:49], v[236:239], v[160:163], v[46:49]
	v_mfma_f32_16x16x32_bf16 v[42:45], v[236:239], v[164:167], v[42:45]
	v_mfma_f32_16x16x32_bf16 v[38:41], v[236:239], v[168:171], v[38:41]
	v_mfma_f32_16x16x32_bf16 v[34:37], v[236:239], v[232:235], v[34:37]
	s_add_i32 m0, s46, 0x2000
	s_nop 0
	buffer_load_dwordx4 v131, s[64:67], s47 offen lds
	v_mfma_f32_16x16x32_bf16 v[30:33], v[240:243], v[160:163], v[30:33]
	v_mfma_f32_16x16x32_bf16 v[26:29], v[240:243], v[164:167], v[26:29]
	v_mfma_f32_16x16x32_bf16 v[22:25], v[240:243], v[168:171], v[22:25]
	v_mfma_f32_16x16x32_bf16 v[18:21], v[240:243], v[232:235], v[18:21]
	s_add_i32 m0, s46, 0xa000
	s_nop 0
	buffer_load_dwordx4 v248, s[12:15], s47 offen lds
	v_mfma_f32_16x16x32_bf16 v[14:17], v[244:247], v[160:163], v[14:17]
	v_mfma_f32_16x16x32_bf16 v[10:13], v[244:247], v[164:167], v[10:13]
	v_mfma_f32_16x16x32_bf16 v[6:9], v[244:247], v[168:171], v[6:9]
	v_mfma_f32_16x16x32_bf16 v[2:5], v[244:247], v[232:235], v[2:5]
	s_add_i32 m0, s46, 0x4000
	s_add_i32 s47, s34, s45
	buffer_load_dwordx4 v131, s[64:67], s47 offen lds
	ds_read_b128 v[160:163], v228 offset:0x1000
	v_xor_b32_e32 v176, 64, v228
.Lrot1_mid_l:
	s_waitcnt lgkmcnt(2)
	v_mfma_f32_16x16x32_bf16 v[126:129], v[152:155], v[134:137], v[126:129]
	v_mfma_f32_16x16x32_bf16 v[122:125], v[152:155], v[138:141], v[122:125]
	v_mfma_f32_16x16x32_bf16 v[118:121], v[152:155], v[144:147], v[118:121]
	v_mfma_f32_16x16x32_bf16 v[114:117], v[152:155], v[148:151], v[114:117]
	s_add_i32 m0, s46, 0xc000
	s_nop 0
	buffer_load_dwordx4 v248, s[12:15], s47 offen lds
	ds_read_b128 v[152:155], v228 offset:0x1800
	s_waitcnt lgkmcnt(2)
	v_mfma_f32_16x16x32_bf16 v[110:113], v[156:159], v[134:137], v[110:113]
	v_mfma_f32_16x16x32_bf16 v[106:109], v[156:159], v[138:141], v[106:109]
	v_mfma_f32_16x16x32_bf16 v[102:105], v[156:159], v[144:147], v[102:105]
	v_mfma_f32_16x16x32_bf16 v[98:101], v[156:159], v[148:151], v[98:101]
	s_add_i32 m0, s46, 0x6000
	s_add_i32 s47, s37, s45
	buffer_load_dwordx4 v131, s[64:67], s47 offen lds
	ds_read_b128 v[156:159], v228 offset:0x2000
	s_waitcnt lgkmcnt(2)
	v_mfma_f32_16x16x32_bf16 v[94:97], v[160:163], v[134:137], v[94:97]
	v_mfma_f32_16x16x32_bf16 v[90:93], v[160:163], v[138:141], v[90:93]
	v_mfma_f32_16x16x32_bf16 v[86:89], v[160:163], v[144:147], v[86:89]
	v_mfma_f32_16x16x32_bf16 v[82:85], v[160:163], v[148:151], v[82:85]
	s_add_i32 m0, s46, 0xe000
	s_nop 0
	buffer_load_dwordx4 v248, s[12:15], s47 offen lds
	ds_read_b128 v[160:163], v228 offset:0x2800
	s_waitcnt lgkmcnt(2)
	v_mfma_f32_16x16x32_bf16 v[78:81], v[152:155], v[134:137], v[78:81]
	v_mfma_f32_16x16x32_bf16 v[74:77], v[152:155], v[138:141], v[74:77]
	v_mfma_f32_16x16x32_bf16 v[70:73], v[152:155], v[144:147], v[70:73]
	v_mfma_f32_16x16x32_bf16 v[66:69], v[152:155], v[148:151], v[66:69]
	ds_read_b128 v[152:155], v228 offset:0x3000
	s_waitcnt lgkmcnt(2)
	v_mfma_f32_16x16x32_bf16 v[62:65], v[156:159], v[134:137], v[62:65]
	v_mfma_f32_16x16x32_bf16 v[58:61], v[156:159], v[138:141], v[58:61]
	v_mfma_f32_16x16x32_bf16 v[54:57], v[156:159], v[144:147], v[54:57]
	v_mfma_f32_16x16x32_bf16 v[50:53], v[156:159], v[148:151], v[50:53]
	ds_read_b128 v[156:159], v228 offset:0x3800
	s_waitcnt lgkmcnt(2)
	v_xor_b32_e32 v0, 64, v229
	v_mfma_f32_16x16x32_bf16 v[46:49], v[160:163], v[134:137], v[46:49]
	v_mfma_f32_16x16x32_bf16 v[42:45], v[160:163], v[138:141], v[42:45]
	v_mfma_f32_16x16x32_bf16 v[38:41], v[160:163], v[144:147], v[38:41]
	v_mfma_f32_16x16x32_bf16 v[34:37], v[160:163], v[148:151], v[34:37]
	ds_read_b128 v[160:163], v0 offset:0
	ds_read_b128 v[164:167], v0 offset:0x800
	ds_read_b128 v[168:171], v0 offset:0x1000
	s_waitcnt lgkmcnt(4)
	v_mfma_f32_16x16x32_bf16 v[30:33], v[152:155], v[134:137], v[30:33]
	v_mfma_f32_16x16x32_bf16 v[26:29], v[152:155], v[138:141], v[26:29]
	v_mfma_f32_16x16x32_bf16 v[22:25], v[152:155], v[144:147], v[22:25]
	v_mfma_f32_16x16x32_bf16 v[18:21], v[152:155], v[148:151], v[18:21]
	ds_read_b128 v[232:235], v0 offset:0x1800
	ds_read_b128 v[172:175], v176 offset:0
	ds_read_b128 v[202:205], v176 offset:0x800
	s_waitcnt lgkmcnt(6)
	v_mfma_f32_16x16x32_bf16 v[14:17], v[156:159], v[134:137], v[14:17]
	v_mfma_f32_16x16x32_bf16 v[10:13], v[156:159], v[138:141], v[10:13]
	v_mfma_f32_16x16x32_bf16 v[6:9], v[156:159], v[144:147], v[6:9]
	v_mfma_f32_16x16x32_bf16 v[2:5], v[156:159], v[148:151], v[2:5]
	ds_read_b128 v[134:137], v176 offset:0x1000
	ds_read_b128 v[236:239], v176 offset:0x2800
	s_waitcnt lgkmcnt(3)
	v_mfma_f32_16x16x32_bf16 v[126:129], v[172:175], v[160:163], v[126:129]
	v_mfma_f32_16x16x32_bf16 v[122:125], v[172:175], v[164:167], v[122:125]
	v_mfma_f32_16x16x32_bf16 v[118:121], v[172:175], v[168:171], v[118:121]
	v_mfma_f32_16x16x32_bf16 v[114:117], v[172:175], v[232:235], v[114:117]
	ds_read_b128 v[138:141], v176 offset:0x1800
	ds_read_b128 v[240:243], v176 offset:0x3000
	s_waitcnt lgkmcnt(4)
	v_mfma_f32_16x16x32_bf16 v[110:113], v[202:205], v[160:163], v[110:113]
	v_mfma_f32_16x16x32_bf16 v[106:109], v[202:205], v[164:167], v[106:109]
	v_mfma_f32_16x16x32_bf16 v[102:105], v[202:205], v[168:171], v[102:105]
	v_mfma_f32_16x16x32_bf16 v[98:101], v[202:205], v[232:235], v[98:101]
	ds_read_b128 v[144:147], v176 offset:0x2000
	ds_read_b128 v[244:247], v176 offset:0x3800
	s_waitcnt lgkmcnt(5)
	v_mfma_f32_16x16x32_bf16 v[94:97], v[134:137], v[160:163], v[94:97]
	v_mfma_f32_16x16x32_bf16 v[90:93], v[134:137], v[164:167], v[90:93]
	v_mfma_f32_16x16x32_bf16 v[86:89], v[134:137], v[168:171], v[86:89]
	v_mfma_f32_16x16x32_bf16 v[82:85], v[134:137], v[232:235], v[82:85]
	s_waitcnt lgkmcnt(3)
	v_mfma_f32_16x16x32_bf16 v[78:81], v[138:141], v[160:163], v[78:81]
	v_mfma_f32_16x16x32_bf16 v[74:77], v[138:141], v[164:167], v[74:77]
	v_mfma_f32_16x16x32_bf16 v[70:73], v[138:141], v[168:171], v[70:73]
	v_mfma_f32_16x16x32_bf16 v[66:69], v[138:141], v[232:235], v[66:69]
	s_waitcnt lgkmcnt(1)
	v_mfma_f32_16x16x32_bf16 v[62:65], v[144:147], v[160:163], v[62:65]
	v_mfma_f32_16x16x32_bf16 v[58:61], v[144:147], v[164:167], v[58:61]
	v_mfma_f32_16x16x32_bf16 v[54:57], v[144:147], v[168:171], v[54:57]
	v_mfma_f32_16x16x32_bf16 v[50:53], v[144:147], v[232:235], v[50:53]
	s_setprio 0
	s_waitcnt lgkmcnt(0)
	s_waitcnt vmcnt(0)
	s_add_i32 s44, s44, 0x10000
	s_addk_i32 s45, 0x80
	s_add_i32 s41, s41, 1
	s_and_b32 s2, s44, 0x10000
	s_cmp_ge_u32 s41, s24
	s_barrier
	s_cbranch_scc0 .Lrot1_top_l

.LBB0_429:
	s_cmp_eq_u32 s15, 0x60800
	s_mov_b32 s2, 0x10000
	s_and_b32 s2, s13, 0x10000
	s_xor_b32 s10, s2, 0x10000
	s_add_i32 s35, s22, s10
	s_add_i32 s36, s15, 0xfffa0000
	s_add_i32 s37, s35, 0x8000
	s_mov_b32 s10, s66
	s_mov_b32 s11, s67
	s_waitcnt lgkmcnt(0)
	v_add_u32_e32 v228, s2, v207
	v_add_u32_e32 v229, s2, v204
	ds_read_b128 v[50:53], v229 offset:0
	ds_read_b128 v[54:57], v229 offset:0x800
	ds_read_b128 v[58:61], v229 offset:0x1000
	ds_read_b128 v[78:81], v229 offset:0x1800
	ds_read_b128 v[98:101], v228 offset:0
	ds_read_b128 v[118:121], v228 offset:0x800
	s_setprio 1
	s_mov_b32 m0, s35
	s_nop 0
	buffer_load_dwordx4 v201, s[64:67], s36 offen lds
	s_mov_b32 m0, s37
	s_nop 0
	buffer_load_dwordx4 v248, s[8:11], s36 offen lds
	s_add_i32 m0, s35, 0x2000
	s_add_i32 s36, s15, 0xfffc0000
	buffer_load_dwordx4 v201, s[64:67], s36 offen lds
	s_add_i32 m0, s35, 0xa000
	s_nop 0
	buffer_load_dwordx4 v248, s[8:11], s36 offen lds
	s_add_i32 m0, s35, 0x4000
	s_add_i32 s36, s15, 0xfffe0000
	buffer_load_dwordx4 v201, s[64:67], s36 offen lds
	ds_read_b128 v[138:141], v228 offset:0x1000
	v_xor_b32_e32 v208, 64, v228
	s_waitcnt lgkmcnt(2)
	v_mfma_f32_16x16x32_bf16 v[150:153], v[98:101], v[50:53], 0
	v_mfma_f32_16x16x32_bf16 v[154:157], v[98:101], v[54:57], 0
	v_mfma_f32_16x16x32_bf16 v[142:145], v[98:101], v[58:61], 0
	v_mfma_f32_16x16x32_bf16 v[98:101], v[98:101], v[78:81], 0
	s_add_i32 m0, s35, 0xc000
	s_nop 0
	buffer_load_dwordx4 v248, s[8:11], s36 offen lds
	ds_read_b128 v[146:149], v228 offset:0x1800
	s_waitcnt lgkmcnt(2)
	v_mfma_f32_16x16x32_bf16 v[130:133], v[118:121], v[50:53], 0
	v_mfma_f32_16x16x32_bf16 v[134:137], v[118:121], v[54:57], 0
	v_mfma_f32_16x16x32_bf16 v[122:125], v[118:121], v[58:61], 0
	v_mfma_f32_16x16x32_bf16 v[118:121], v[118:121], v[78:81], 0
	s_add_i32 m0, s35, 0x6000
	s_nop 0
	buffer_load_dwordx4 v201, s[64:67], s15 offen lds
	ds_read_b128 v[126:129], v228 offset:0x2000
	s_waitcnt lgkmcnt(2)
	v_mfma_f32_16x16x32_bf16 v[110:113], v[138:141], v[50:53], 0
	v_mfma_f32_16x16x32_bf16 v[114:117], v[138:141], v[54:57], 0
	v_mfma_f32_16x16x32_bf16 v[102:105], v[138:141], v[58:61], 0
	v_mfma_f32_16x16x32_bf16 v[106:109], v[138:141], v[78:81], 0
	s_add_i32 m0, s35, 0xe000
	s_nop 0
	buffer_load_dwordx4 v248, s[8:11], s15 offen lds
	ds_read_b128 v[138:141], v228 offset:0x2800
	s_waitcnt lgkmcnt(2)
	v_mfma_f32_16x16x32_bf16 v[90:93], v[146:149], v[50:53], 0
	v_mfma_f32_16x16x32_bf16 v[94:97], v[146:149], v[54:57], 0
	v_mfma_f32_16x16x32_bf16 v[82:85], v[146:149], v[58:61], 0
	v_mfma_f32_16x16x32_bf16 v[86:89], v[146:149], v[78:81], 0
	ds_read_b128 v[146:149], v228 offset:0x3000
	s_waitcnt lgkmcnt(2)
	v_mfma_f32_16x16x32_bf16 v[70:73], v[126:129], v[50:53], 0
	v_mfma_f32_16x16x32_bf16 v[74:77], v[126:129], v[54:57], 0
	v_mfma_f32_16x16x32_bf16 v[62:65], v[126:129], v[58:61], 0
	v_mfma_f32_16x16x32_bf16 v[66:69], v[126:129], v[78:81], 0
	ds_read_b128 v[126:129], v228 offset:0x3800
	s_waitcnt lgkmcnt(2)
	v_xor_b32_e32 v166, 64, v229
	v_mfma_f32_16x16x32_bf16 v[42:45], v[138:141], v[50:53], 0
	v_mfma_f32_16x16x32_bf16 v[46:49], v[138:141], v[54:57], 0
	v_mfma_f32_16x16x32_bf16 v[34:37], v[138:141], v[58:61], 0
	v_mfma_f32_16x16x32_bf16 v[38:41], v[138:141], v[78:81], 0
	ds_read_b128 v[138:141], v166 offset:0
	ds_read_b128 v[158:161], v166 offset:0x800
	ds_read_b128 v[162:165], v166 offset:0x1000
	s_waitcnt lgkmcnt(4)
	v_mfma_f32_16x16x32_bf16 v[26:29], v[146:149], v[50:53], 0
	v_mfma_f32_16x16x32_bf16 v[30:33], v[146:149], v[54:57], 0
	v_mfma_f32_16x16x32_bf16 v[18:21], v[146:149], v[58:61], 0
	v_mfma_f32_16x16x32_bf16 v[22:25], v[146:149], v[78:81], 0
	ds_read_b128 v[166:169], v166 offset:0x1800
	ds_read_b128 v[146:149], v208 offset:0
	ds_read_b128 v[174:177], v208 offset:0x800
	s_waitcnt lgkmcnt(6)
	v_mfma_f32_16x16x32_bf16 v[10:13], v[126:129], v[50:53], 0
	v_mfma_f32_16x16x32_bf16 v[14:17], v[126:129], v[54:57], 0
	v_mfma_f32_16x16x32_bf16 v[2:5], v[126:129], v[58:61], 0
	v_mfma_f32_16x16x32_bf16 v[6:9], v[126:129], v[78:81], 0
	ds_read_b128 v[50:53], v208 offset:0x1000
	ds_read_b128 v[232:235], v208 offset:0x2800
	s_waitcnt lgkmcnt(3)
	v_mfma_f32_16x16x32_bf16 v[150:153], v[146:149], v[138:141], v[150:153]
	v_mfma_f32_16x16x32_bf16 v[154:157], v[146:149], v[158:161], v[154:157]
	v_mfma_f32_16x16x32_bf16 v[142:145], v[146:149], v[162:165], v[142:145]
	v_mfma_f32_16x16x32_bf16 v[146:149], v[146:149], v[166:169], v[98:101]
	ds_read_b128 v[54:57], v208 offset:0x1800
	ds_read_b128 v[236:239], v208 offset:0x3000
	s_waitcnt lgkmcnt(4)
	v_mfma_f32_16x16x32_bf16 v[130:133], v[174:177], v[138:141], v[130:133]
	v_mfma_f32_16x16x32_bf16 v[134:137], v[174:177], v[158:161], v[134:137]
	v_mfma_f32_16x16x32_bf16 v[122:125], v[174:177], v[162:165], v[122:125]
	v_mfma_f32_16x16x32_bf16 v[126:129], v[174:177], v[166:169], v[118:121]
	ds_read_b128 v[58:61], v208 offset:0x2000
	ds_read_b128 v[240:243], v208 offset:0x3800
	s_waitcnt lgkmcnt(5)
	v_mfma_f32_16x16x32_bf16 v[110:113], v[50:53], v[138:141], v[110:113]
	v_mfma_f32_16x16x32_bf16 v[114:117], v[50:53], v[158:161], v[114:117]
	v_mfma_f32_16x16x32_bf16 v[102:105], v[50:53], v[162:165], v[102:105]
	v_mfma_f32_16x16x32_bf16 v[106:109], v[50:53], v[166:169], v[106:109]
	s_waitcnt lgkmcnt(3)
	v_mfma_f32_16x16x32_bf16 v[90:93], v[54:57], v[138:141], v[90:93]
	v_mfma_f32_16x16x32_bf16 v[94:97], v[54:57], v[158:161], v[94:97]
	v_mfma_f32_16x16x32_bf16 v[82:85], v[54:57], v[162:165], v[82:85]
	v_mfma_f32_16x16x32_bf16 v[86:89], v[54:57], v[166:169], v[86:89]
	s_waitcnt lgkmcnt(1)
	v_mfma_f32_16x16x32_bf16 v[70:73], v[58:61], v[138:141], v[70:73]
	v_mfma_f32_16x16x32_bf16 v[74:77], v[58:61], v[158:161], v[74:77]
	v_mfma_f32_16x16x32_bf16 v[62:65], v[58:61], v[162:165], v[62:65]
	v_mfma_f32_16x16x32_bf16 v[66:69], v[58:61], v[166:169], v[66:69]
	s_setprio 0
	s_waitcnt lgkmcnt(0)
	s_waitcnt vmcnt(0)
	s_add_i32 s13, s13, 0x10000
	s_addk_i32 s15, 0x80
	s_cmp_eq_u32 s15, 0x60800
	s_mov_b32 s2, 0x10000
	s_barrier
	s_cbranch_scc0 .Lrot0_top_l
	s_branch .Lrot0_top_n
.Lrot0_top_l:
	s_and_b32 s2, s13, 0x10000
	s_xor_b32 s10, s2, 0x10000
	s_add_i32 s35, s22, s10
	s_add_i32 s36, s15, 0xfffa0000
	s_add_i32 s37, s35, 0x8000
	s_mov_b32 s10, s66
	s_mov_b32 s11, s67
	v_add_u32_e32 v228, s2, v207
	v_add_u32_e32 v229, s2, v204
	ds_read_b128 v[50:53], v229 offset:0
	ds_read_b128 v[54:57], v229 offset:0x800
	ds_read_b128 v[58:61], v229 offset:0x1000
	ds_read_b128 v[78:81], v229 offset:0x1800
	ds_read_b128 v[98:101], v228 offset:0
	ds_read_b128 v[118:121], v228 offset:0x800
	s_setprio 1
	s_mov_b32 m0, s35
	s_nop 0
	buffer_load_dwordx4 v201, s[64:67], s36 offen lds
	s_mov_b32 m0, s37
	s_nop 0
	buffer_load_dwordx4 v248, s[8:11], s36 offen lds
	v_mfma_f32_16x16x32_bf16 v[42:45], v[232:235], v[138:141], v[42:45]
	v_mfma_f32_16x16x32_bf16 v[46:49], v[232:235], v[158:161], v[46:49]
	v_mfma_f32_16x16x32_bf16 v[34:37], v[232:235], v[162:165], v[34:37]
	v_mfma_f32_16x16x32_bf16 v[38:41], v[232:235], v[166:169], v[38:41]
	s_add_i32 m0, s35, 0x2000
	s_add_i32 s36, s15, 0xfffc0000
	buffer_load_dwordx4 v201, s[64:67], s36 offen lds
	v_mfma_f32_16x16x32_bf16 v[26:29], v[236:239], v[138:141], v[26:29]
	v_mfma_f32_16x16x32_bf16 v[30:33], v[236:239], v[158:161], v[30:33]
	v_mfma_f32_16x16x32_bf16 v[18:21], v[236:239], v[162:165], v[18:21]
	v_mfma_f32_16x16x32_bf16 v[22:25], v[236:239], v[166:169], v[22:25]
	s_add_i32 m0, s35, 0xa000
	s_nop 0
	buffer_load_dwordx4 v248, s[8:11], s36 offen lds
	v_mfma_f32_16x16x32_bf16 v[10:13], v[240:243], v[138:141], v[10:13]
	v_mfma_f32_16x16x32_bf16 v[14:17], v[240:243], v[158:161], v[14:17]
	v_mfma_f32_16x16x32_bf16 v[2:5], v[240:243], v[162:165], v[2:5]
	v_mfma_f32_16x16x32_bf16 v[6:9], v[240:243], v[166:169], v[6:9]
	s_add_i32 m0, s35, 0x4000
	s_add_i32 s36, s15, 0xfffe0000
	buffer_load_dwordx4 v201, s[64:67], s36 offen lds
	ds_read_b128 v[138:141], v228 offset:0x1000
	v_xor_b32_e32 v208, 64, v228
.Lrot0_mid_l:
	s_waitcnt lgkmcnt(2)
	v_mfma_f32_16x16x32_bf16 v[150:153], v[98:101], v[50:53], v[150:153]
	v_mfma_f32_16x16x32_bf16 v[154:157], v[98:101], v[54:57], v[154:157]
	v_mfma_f32_16x16x32_bf16 v[142:145], v[98:101], v[58:61], v[142:145]
	v_mfma_f32_16x16x32_bf16 v[98:101], v[98:101], v[78:81], v[146:149]
	s_add_i32 m0, s35, 0xc000
	s_nop 0
	buffer_load_dwordx4 v248, s[8:11], s36 offen lds
	ds_read_b128 v[146:149], v228 offset:0x1800
	s_waitcnt lgkmcnt(2)
	v_mfma_f32_16x16x32_bf16 v[130:133], v[118:121], v[50:53], v[130:133]
	v_mfma_f32_16x16x32_bf16 v[134:137], v[118:121], v[54:57], v[134:137]
	v_mfma_f32_16x16x32_bf16 v[122:125], v[118:121], v[58:61], v[122:125]
	v_mfma_f32_16x16x32_bf16 v[118:121], v[118:121], v[78:81], v[126:129]
	s_add_i32 m0, s35, 0x6000
	s_nop 0
	buffer_load_dwordx4 v201, s[64:67], s15 offen lds
	ds_read_b128 v[126:129], v228 offset:0x2000
	s_waitcnt lgkmcnt(2)
	v_mfma_f32_16x16x32_bf16 v[110:113], v[138:141], v[50:53], v[110:113]
	v_mfma_f32_16x16x32_bf16 v[114:117], v[138:141], v[54:57], v[114:117]
	v_mfma_f32_16x16x32_bf16 v[102:105], v[138:141], v[58:61], v[102:105]
	v_mfma_f32_16x16x32_bf16 v[106:109], v[138:141], v[78:81], v[106:109]
	s_add_i32 m0, s35, 0xe000
	s_nop 0
	buffer_load_dwordx4 v248, s[8:11], s15 offen lds
	ds_read_b128 v[138:141], v228 offset:0x2800
	s_waitcnt lgkmcnt(2)
	v_mfma_f32_16x16x32_bf16 v[90:93], v[146:149], v[50:53], v[90:93]
	v_mfma_f32_16x16x32_bf16 v[94:97], v[146:149], v[54:57], v[94:97]
	v_mfma_f32_16x16x32_bf16 v[82:85], v[146:149], v[58:61], v[82:85]
	v_mfma_f32_16x16x32_bf16 v[86:89], v[146:149], v[78:81], v[86:89]
	ds_read_b128 v[146:149], v228 offset:0x3000
	s_waitcnt lgkmcnt(2)
	v_mfma_f32_16x16x32_bf16 v[70:73], v[126:129], v[50:53], v[70:73]
	v_mfma_f32_16x16x32_bf16 v[74:77], v[126:129], v[54:57], v[74:77]
	v_mfma_f32_16x16x32_bf16 v[62:65], v[126:129], v[58:61], v[62:65]
	v_mfma_f32_16x16x32_bf16 v[66:69], v[126:129], v[78:81], v[66:69]
	ds_read_b128 v[126:129], v228 offset:0x3800
	s_waitcnt lgkmcnt(2)
	v_xor_b32_e32 v166, 64, v229
	v_mfma_f32_16x16x32_bf16 v[42:45], v[138:141], v[50:53], v[42:45]
	v_mfma_f32_16x16x32_bf16 v[46:49], v[138:141], v[54:57], v[46:49]
	v_mfma_f32_16x16x32_bf16 v[34:37], v[138:141], v[58:61], v[34:37]
	v_mfma_f32_16x16x32_bf16 v[38:41], v[138:141], v[78:81], v[38:41]
	ds_read_b128 v[138:141], v166 offset:0
	ds_read_b128 v[158:161], v166 offset:0x800
	ds_read_b128 v[162:165], v166 offset:0x1000
	s_waitcnt lgkmcnt(4)
	v_mfma_f32_16x16x32_bf16 v[26:29], v[146:149], v[50:53], v[26:29]
	v_mfma_f32_16x16x32_bf16 v[30:33], v[146:149], v[54:57], v[30:33]
	v_mfma_f32_16x16x32_bf16 v[18:21], v[146:149], v[58:61], v[18:21]
	v_mfma_f32_16x16x32_bf16 v[22:25], v[146:149], v[78:81], v[22:25]
	ds_read_b128 v[166:169], v166 offset:0x1800
	ds_read_b128 v[146:149], v208 offset:0
	ds_read_b128 v[174:177], v208 offset:0x800
	s_waitcnt lgkmcnt(6)
	v_mfma_f32_16x16x32_bf16 v[10:13], v[126:129], v[50:53], v[10:13]
	v_mfma_f32_16x16x32_bf16 v[14:17], v[126:129], v[54:57], v[14:17]
	v_mfma_f32_16x16x32_bf16 v[2:5], v[126:129], v[58:61], v[2:5]
	v_mfma_f32_16x16x32_bf16 v[6:9], v[126:129], v[78:81], v[6:9]
	ds_read_b128 v[50:53], v208 offset:0x1000
	ds_read_b128 v[232:235], v208 offset:0x2800
	s_waitcnt lgkmcnt(3)
	v_mfma_f32_16x16x32_bf16 v[150:153], v[146:149], v[138:141], v[150:153]
	v_mfma_f32_16x16x32_bf16 v[154:157], v[146:149], v[158:161], v[154:157]
	v_mfma_f32_16x16x32_bf16 v[142:145], v[146:149], v[162:165], v[142:145]
	v_mfma_f32_16x16x32_bf16 v[146:149], v[146:149], v[166:169], v[98:101]
	ds_read_b128 v[54:57], v208 offset:0x1800
	ds_read_b128 v[236:239], v208 offset:0x3000
	s_waitcnt lgkmcnt(4)
	v_mfma_f32_16x16x32_bf16 v[130:133], v[174:177], v[138:141], v[130:133]
	v_mfma_f32_16x16x32_bf16 v[134:137], v[174:177], v[158:161], v[134:137]
	v_mfma_f32_16x16x32_bf16 v[122:125], v[174:177], v[162:165], v[122:125]
	v_mfma_f32_16x16x32_bf16 v[126:129], v[174:177], v[166:169], v[118:121]
	ds_read_b128 v[58:61], v208 offset:0x2000
	ds_read_b128 v[240:243], v208 offset:0x3800
	s_waitcnt lgkmcnt(5)
	v_mfma_f32_16x16x32_bf16 v[110:113], v[50:53], v[138:141], v[110:113]
	v_mfma_f32_16x16x32_bf16 v[114:117], v[50:53], v[158:161], v[114:117]
	v_mfma_f32_16x16x32_bf16 v[102:105], v[50:53], v[162:165], v[102:105]
	v_mfma_f32_16x16x32_bf16 v[106:109], v[50:53], v[166:169], v[106:109]
	s_waitcnt lgkmcnt(3)
	v_mfma_f32_16x16x32_bf16 v[90:93], v[54:57], v[138:141], v[90:93]
	v_mfma_f32_16x16x32_bf16 v[94:97], v[54:57], v[158:161], v[94:97]
	v_mfma_f32_16x16x32_bf16 v[82:85], v[54:57], v[162:165], v[82:85]
	v_mfma_f32_16x16x32_bf16 v[86:89], v[54:57], v[166:169], v[86:89]
	s_waitcnt lgkmcnt(1)
	v_mfma_f32_16x16x32_bf16 v[70:73], v[58:61], v[138:141], v[70:73]
	v_mfma_f32_16x16x32_bf16 v[74:77], v[58:61], v[158:161], v[74:77]
	v_mfma_f32_16x16x32_bf16 v[62:65], v[58:61], v[162:165], v[62:65]
	v_mfma_f32_16x16x32_bf16 v[66:69], v[58:61], v[166:169], v[66:69]
	s_setprio 0
	s_waitcnt lgkmcnt(0)
	s_waitcnt vmcnt(0)
	s_add_i32 s13, s13, 0x10000
	s_addk_i32 s15, 0x80
	s_cmp_eq_u32 s15, 0x60800
	s_mov_b32 s2, 0x10000
	s_barrier
	s_cbranch_scc0 .Lrot0_top_l
